# static priority for waves 4-7 scoped to the GEMM phases; inside attention both wave groups drop to priority 0 outside their MFMA sections, static raise restored at phase end
# speedup vs baseline: 1.0060x; 1.0060x over previous
.Lat_all_done:
	s_cmp_eq_u32 s35, 0
	s_cbranch_scc1 .Lat_pr_end
	s_setprio 1
